# m2_c final segment: h-state fragment loads through an 11-quad ring issued up front, d_skip via scalar loads, vmcnt recounted
# speedup vs baseline: 1.0605x; 1.0052x over previous
; #define LAS __attribute__((address_space(3)))
; #define MFMA16(a, b, c) __builtin_amdgcn_mfma_f32_16x16x32_bf16((a), (b), (c), 0, 0, 0)
; __device__ void m2_c_unit(LAS unsigned char* lds, KP& P_, int l, int bc, int grp) {
;     ...
;     f32x4 yv[6], nwv[6];
; #pragma unroll
;     for (int i = 0; i < 6; ++i) nwv[i] = *(const f32x4*)(p.in[10] + l * 384 + grp * 192 + (ph * 6 + i) * 16 + fq * 4);
;     { bf16x8 cf[4];
; #pragma unroll
;       for (int ks = 0; ks < 4; ++ks) cf[ks] = *(const LAS bf16x8*)(CM + tq * 136 + ks * 32 + fq * 8);
;       const bf16_t* stm = (const bf16_t*)(p.ws + WS_STM); float ssq = 0.f;
;       u32x2 zraw[6];
; #pragma unroll
;       for (int i = 0; i < 6; ++i) zraw[i] = *(const u32x2*)(proj + orow * NPROJ + C_Z + grp * 192 + (ph * 6 + i) * 16 + fq * 4);
;       bf16x8 hf[4];
; #pragma unroll
;       for (int ks = 0; ks < 4; ++ks) hf[ks] = *(const bf16x8*)(stm + (((size_t)bc * 6 + grp * 3 + ((ph * 6) >> 2)) * 64 + ((ph * 6) & 3) * 16 + fr) * 128 + ks * 32 + fq * 8);
; #pragma unroll
;       for (int i = 0; i < 6; ++i) { const int pt = ph * 6 + i, hh = pt >> 2, head = grp * 3 + hh;
;           f32x4 ad = (f32x4){0.f, 0.f, 0.f, 0.f}, ao = (f32x4){0.f, 0.f, 0.f, 0.f};
;           bf16x8 hc[4];
; #pragma unroll
;           for (int ks = 0; ks < 4; ++ks) hc[ks] = hf[ks];
;           if (i < 5) { const int pn = pt + 1;
; #pragma unroll
;               for (int ks = 0; ks < 4; ++ks) hf[ks] = *(const bf16x8*)(stm + (((size_t)bc * 6 + grp * 3 + (pn >> 2)) * 64 + (pn & 3) * 16 + fr) * 128 + ks * 32 + fq * 8); }
; #pragma unroll
;           for (int ks = 0; ks < 2; ++ks) { const unsigned ta = xn_base + (unsigned)((32 * ks + 8 * fq + (fr >> 2)) * 400 + (16 * pt + 4 * (fr & 3)) * 2);
;               const bf16x8 a = tr_frag(ta, ta + 1600u), b = *(const LAS bf16x8*)(PH + hh * 4608 + tq * 72 + ks * 32 + fq * 8); ad = MFMA16(a, b, ad); }
; #pragma unroll
;           for (int ks = 0; ks < 4; ++ks) ao = MFMA16(hc[ks], cf[ks], ao);
;           const float ea = __expf(acs[hh * 64 + tq]), dsk = p.in[9][l * 6 + head]; const int pch = pt * 16 + fq * 4;
.LBB0_477:
	s_or_b64 exec, exec, s[14:15]
	v_cvt_pk_bf16_f32 v10, v16, v15
	v_cvt_pk_bf16_f32 v11, v9, v8
	ds_write_b64 v13, v[10:11] offset:18432
	s_waitcnt lgkmcnt(0)
	s_barrier
	s_load_dwordx4 s[44:47], s[24:25], 0x48
	s_mul_i32 s14, s13, 0x180
	s_ashr_i32 s15, s14, 31
	s_ashr_i32 s97, s96, 31
	s_lshl_b64 s[14:15], s[14:15], 2
	s_waitcnt lgkmcnt(0)
	s_mul_i32 s62, s13, 6
	s_mul_i32 s63, s22, 3
	s_add_i32 s62, s62, s63
	s_lshl_b32 s62, s62, 2
	s_add_u32 s62, s44, s62
	s_addc_u32 s63, s45, 0
	s_load_dword s64, s[62:63], 0x0
	s_load_dword s65, s[62:63], 0x4
	s_load_dword s66, s[62:63], 0x8
	s_add_u32 s12, s46, s14
	v_ashrrev_i32_e32 v143, 8, v2
	s_addc_u32 s15, s47, s15
	s_lshl_b32 s14, s23, 2
	v_lshlrev_b32_e32 v0, 4, v0
	s_add_u32 s14, s12, s14
	v_mul_i32_i24_e32 v52, 6, v143
	v_and_or_b32 v144, v0, 48, v142
	s_addc_u32 s15, s15, 0
	v_lshlrev_b32_e32 v0, 2, v105
	v_mul_i32_i24_e32 v90, 0x60, v143
	v_or_b32_e32 v112, 1, v52
	v_lshl_add_u64 v[8:9], s[14:15], 0, v[0:1]
	v_ashrrev_i32_e32 v91, 31, v90
	v_lshlrev_b32_e32 v88, 4, v112
	v_mad_i32_i24 v122, v143, 6, 2
	v_lshl_add_u64 v[10:11], v[90:91], 2, v[8:9]
	v_ashrrev_i32_e32 v89, 31, v88
	v_lshlrev_b32_e32 v86, 4, v122
	v_mad_i32_i24 v128, v143, 6, 3
	global_load_dwordx4 v[28:31], v[10:11], off
	v_lshl_add_u64 v[10:11], v[88:89], 2, v[8:9]
	v_ashrrev_i32_e32 v87, 31, v86
	v_lshlrev_b32_e32 v84, 4, v128
	v_mad_i32_i24 v146, v143, 6, 4
	v_mad_i32_i24 v145, v143, 6, 5
	s_lshl_b64 s[14:15], s[96:97], 6
	global_load_dwordx4 v[24:27], v[10:11], off
	v_lshl_add_u64 v[10:11], v[86:87], 2, v[8:9]
	v_ashrrev_i32_e32 v85, 31, v84
	v_lshlrev_b32_e32 v82, 4, v146
	v_lshlrev_b32_e32 v80, 4, v145
	v_or_b32_e32 v92, s14, v144
	v_mov_b64_e32 v[48:49], s[6:7]
	global_load_dwordx4 v[20:23], v[10:11], off
	v_lshl_add_u64 v[10:11], v[84:85], 2, v[8:9]
	v_ashrrev_i32_e32 v83, 31, v82
	v_ashrrev_i32_e32 v81, 31, v80
	v_mul_u32_u24_e32 v0, 0x110, v144
	v_mad_u64_u32 v[48:49], s[24:25], v92, s9, v[48:49]
	global_load_dwordx4 v[16:19], v[10:11], off
	v_lshl_add_u64 v[10:11], v[82:83], 2, v[8:9]
	v_lshl_add_u64 v[8:9], v[80:81], 2, v[8:9]
	v_add3_u32 v0, 0, v0, v32
	v_mad_i32_i24 v49, s15, v215, v49
	s_lshl_b32 s90, s23, 1
	global_load_dwordx4 v[12:15], v[10:11], off
	v_lshl_add_u64 v[48:49], v[48:49], 0, s[90:91]
	global_load_dwordx4 v[8:11], v[8:9], off
	ds_read_b128 v[32:35], v0 offset:45056
	ds_read_b128 v[36:39], v0 offset:45120
	ds_read_b128 v[40:43], v0 offset:45184
	ds_read_b128 v[44:47], v0 offset:45248
	v_lshlrev_b32_e32 v0, 1, v105
	v_lshl_add_u64 v[48:49], v[48:49], 0, v[0:1]
	v_lshl_add_u64 v[50:51], v[90:91], 1, v[48:49]
	global_load_dwordx2 v[96:97], v[50:51], off offset:3072
	v_lshl_add_u64 v[50:51], v[88:89], 1, v[48:49]
	s_add_u32 s42, s6, 0xcf30000
	global_load_dwordx2 v[108:109], v[50:51], off offset:3072
	v_lshl_add_u64 v[50:51], v[86:87], 1, v[48:49]
	s_addc_u32 s43, s7, 0
	s_mul_i32 s14, s96, 6
	s_mul_i32 s22, s22, 3
	global_load_dwordx2 v[120:121], v[50:51], off offset:3072
	v_lshl_add_u64 v[50:51], v[84:85], 1, v[48:49]
	s_mul_hi_i32 s12, s96, 6
	s_add_u32 s24, s14, s22
	v_ashrrev_i32_e32 v98, 2, v52
	global_load_dwordx2 v[114:115], v[50:51], off offset:3072
	v_lshl_add_u64 v[50:51], v[82:83], 1, v[48:49]
	v_lshl_add_u64 v[48:49], v[80:81], 1, v[48:49]
	s_addc_u32 s25, s12, 0
	v_ashrrev_i32_e32 v99, 31, v98
	global_load_dwordx2 v[102:103], v[50:51], off offset:3072
	global_load_dwordx2 v[94:95], v[48:49], off offset:3072
	v_lshl_add_u64 v[48:49], s[24:25], 0, v[98:99]
	v_lshlrev_b32_e32 v0, 5, v143
	v_lshlrev_b64 v[64:65], 6, v[48:49]
	v_and_b32_e32 v0, 32, v0
	v_or3_b32 v48, v64, v0, v142
	v_mov_b32_e32 v49, v65
	v_lshlrev_b64 v[48:49], 8, v[48:49]
	v_lshl_add_u64 v[48:49], s[42:43], 0, v[48:49]
	v_lshlrev_b32_e32 v0, 1, v3
	v_lshl_add_u64 v[56:57], v[48:49], 0, v[0:1]
	s_mov_b64 s[78:79], 0x1000
	v_lshl_add_u64 v[210:211], v[56:57], 0, s[78:79]
	global_load_dwordx4 v[60:63], v[56:57], off
	global_load_dwordx4 v[52:55], v[56:57], off offset:64
	global_load_dwordx4 v[48:51], v[56:57], off offset:128
	s_nop 0
	global_load_dwordx4 v[56:59], v[56:57], off offset:192
	global_load_dwordx4 v[222:225], v[210:211], off
	global_load_dwordx4 v[226:229], v[210:211], off offset:64
	global_load_dwordx4 v[230:233], v[210:211], off offset:128
	global_load_dwordx4 v[234:237], v[210:211], off offset:192
	v_lshl_add_u64 v[210:211], v[210:211], 0, s[78:79]
	global_load_dwordx4 v[238:241], v[210:211], off
	global_load_dwordx4 v[242:245], v[210:211], off offset:64
	global_load_dwordx4 v[246:249], v[210:211], off offset:128
	global_load_dwordx4 v[162:165], v[210:211], off offset:192
	v_lshl_add_u64 v[210:211], v[210:211], 0, s[78:79]
	global_load_dwordx4 v[166:169], v[210:211], off
	global_load_dwordx4 v[184:187], v[210:211], off offset:64
	global_load_dwordx4 v[188:191], v[210:211], off offset:128
	v_lshlrev_b32_e32 v2, 3, v2
	v_and_b32_e32 v87, 24, v2
	v_mad_u32_u24 v2, v144, s10, 0
	v_add_u32_e32 v104, v2, v0
	v_lshl_add_u64 v[116:117], s[42:43], 0, v[0:1]
	v_lshlrev_b32_e32 v0, 8, v144
	v_add3_u32 v81, v2, v0, v3
	v_and_b32_e32 v0, 48, v88
	v_lshrrev_b32_e32 v66, 2, v142
	v_or3_b32 v64, v64, v0, v142
	v_or_b32_e32 v85, v3, v66
	s_mul_i32 s13, s13, 6
	s_waitcnt lgkmcnt(3)
	s_waitcnt vmcnt(14)
	v_mfma_f32_16x16x32_bf16 v[60:63], v[60:63], v[32:35], 0
	v_lshlrev_b64 v[2:3], 8, v[64:65]
	v_mul_i32_i24_e32 v0, 0xc0, v143
	s_add_i32 s13, s13, s22
	s_waitcnt lgkmcnt(2)
	s_waitcnt vmcnt(13)
; #define LAS __attribute__((address_space(3)))
; __device__ __forceinline__ float bflo(unsigned w) { return __uint_as_float(w << 16); }
; __device__ __forceinline__ float bfhi(unsigned w) { return __uint_as_float(w & 0xffff0000u); }
; __device__ __forceinline__ float siluf_(float x) { return x * __builtin_amdgcn_rcpf(1.0f + __expf(-x)); }
; #define MFMA16(a, b, c) __builtin_amdgcn_mfma_f32_16x16x32_bf16((a), (b), (c), 0, 0, 0)
; __device__ void m2_c_unit(LAS unsigned char* lds, KP& P_, int l, int bc, int grp) {
;     ...
;       for (int i = 0; i < 6; ++i) { const int pt = ph * 6 + i, hh = pt >> 2, head = grp * 3 + hh;
;           f32x4 ad = (f32x4){0.f, 0.f, 0.f, 0.f}, ao = (f32x4){0.f, 0.f, 0.f, 0.f};
;           bf16x8 hc[4];
; #pragma unroll
;           for (int ks = 0; ks < 4; ++ks) hc[ks] = hf[ks];
;           if (i < 5) { const int pn = pt + 1;
; #pragma unroll
;               for (int ks = 0; ks < 4; ++ks) hf[ks] = *(const bf16x8*)(stm + (((size_t)bc * 6 + grp * 3 + (pn >> 2)) * 64 + (pn & 3) * 16 + fr) * 128 + ks * 32 + fq * 8); }
; #pragma unroll
;           for (int ks = 0; ks < 2; ++ks) { const unsigned ta = xn_base + (unsigned)((32 * ks + 8 * fq + (fr >> 2)) * 400 + (16 * pt + 4 * (fr & 3)) * 2);
;               const bf16x8 a = tr_frag(ta, ta + 1600u), b = *(const LAS bf16x8*)(PH + hh * 4608 + tq * 72 + ks * 32 + fq * 8); ad = MFMA16(a, b, ad); }
; #pragma unroll
;           for (int ks = 0; ks < 4; ++ks) ao = MFMA16(hc[ks], cf[ks], ao);
;           const float ea = __expf(acs[hh * 64 + tq]), dsk = p.in[9][l * 6 + head]; const int pch = pt * 16 + fq * 4;
;           const float zv[4] = {bflo(zraw[i].x), bfhi(zraw[i].x), bflo(zraw[i].y), bfhi(zraw[i].y)};
;           f32x4 y;
;           const u32x2 xraw = *(const LAS u32x2*)(XN + tq * 200 + pch); const float xsv[4] = {bflo(xraw.x), bfhi(xraw.x), bflo(xraw.y), bfhi(xraw.y)};
; #pragma unroll
;           for (int j = 0; j < 4; ++j) { y[j] = (ad[j] + ea * ao[j] + dsk * xsv[j]) * siluf_(zv[j]); ssq += y[j] * y[j]; }
;           yv[i] = y; }
	v_mfma_f32_16x16x32_bf16 v[52:55], v[52:55], v[36:39], v[60:63]
	v_lshl_add_u64 v[2:3], v[116:117], 0, v[2:3]
	v_or_b32_e32 v0, v0, v87
	s_movk_i32 s22, 0x190
	v_mad_u32_u24 v2, v85, s22, v0
	v_readlane_b32 s26, v255, 10
	v_mad_u32_u24 v89, v85, s22, v199
	s_movk_i32 s23, 0x2400
	v_add_u32_e32 v3, 0, v2
	v_add_u32_e32 v2, s26, v2
	v_add_u32_e32 v0, v89, v0
	v_mov_b32_e32 v93, s15
	v_mad_u64_u32 v[106:107], s[14:15], v98, s23, v[104:105]
	ds_read_b64_tr_b16 v[124:125], v3
	ds_read_b64_tr_b16 v[126:127], v2
	s_waitcnt lgkmcnt(0)
	v_readfirstlane_b32 s76, v143
	s_cmp_eq_u32 s76, 0
	s_cselect_b32 s70, s64, s65
	s_cselect_b32 s72, s64, s66
	s_cselect_b32 s74, s65, s66
	v_add_u32_e32 v2, 0, v0
	s_waitcnt lgkmcnt(1)
	s_waitcnt vmcnt(12)
	v_mfma_f32_16x16x32_bf16 v[48:51], v[48:51], v[40:43], v[52:55]
	ds_read_b128 v[130:133], v106 offset:62464
	v_add_u32_e32 v0, s26, v0
	ds_read_b64_tr_b16 v[148:149], v2
	ds_read_b64_tr_b16 v[150:151], v0
	s_waitcnt lgkmcnt(0)
	v_add_u32_e32 v2, s13, v98
	v_ashrrev_i32_e32 v3, 31, v2
	v_lshl_add_u64 v[110:111], v[2:3], 2, s[44:45]
	s_waitcnt lgkmcnt(1)
	s_waitcnt vmcnt(11)
	v_mfma_f32_16x16x32_bf16 v[48:51], v[56:59], v[44:47], v[48:51]
	s_add_i32 s12, 0, 0x16300
	v_lshl_add_u32 v83, v144, 2, s12
	v_lshl_add_u32 v91, v98, 8, v83
	ds_read_b32 v0, v91
	ds_read_b128 v[152:155], v106 offset:62528
	s_waitcnt lgkmcnt(2)
	v_mfma_f32_16x16x32_bf16 v[52:55], v[124:127], v[130:133], 0
	s_movk_i32 s12, 0xc0
	v_mad_i32_i24 v2, v143, s12, v81
	ds_read_b64 v[58:59], v2
	s_waitcnt lgkmcnt(2)
	v_mul_f32_e32 v0, 0x3fb8aa3b, v0
	s_waitcnt lgkmcnt(1)
	v_mfma_f32_16x16x32_bf16 v[52:55], v[148:151], v[152:155], v[52:55]
	v_exp_f32_e32 v0, v0
	v_lshlrev_b32_e32 v2, 16, v96
	v_and_b32_e32 v3, 0xffff0000, v96
	v_mul_f32_e32 v57, 0xbfb8aa3b, v2
	v_exp_f32_e32 v57, v57
	s_nop 2
	v_pk_fma_f32 v[48:49], v[48:49], v[0:1], v[52:53] op_sel_hi:[1,0,1]
	v_mul_f32_e32 v52, 0xbfb8aa3b, v3
	v_exp_f32_e32 v52, v52
	v_add_f32_e32 v57, 1.0, v57
	v_rcp_f32_e32 v62, v57
	s_waitcnt lgkmcnt(0)
	v_lshlrev_b32_e32 v60, 16, v58
	v_add_f32_e32 v52, 1.0, v52
	v_rcp_f32_e32 v63, v52
	v_and_b32_e32 v61, 0xffff0000, v58
	v_pk_fma_f32 v[50:51], v[50:51], v[0:1], v[54:55] op_sel_hi:[1,0,1]
	v_lshlrev_b32_e32 v52, 16, v59
	v_pk_mul_f32 v[2:3], v[62:63], v[2:3]
	v_and_b32_e32 v53, 0xffff0000, v59
	v_ashrrev_i32_e32 v118, 2, v122
	v_ashrrev_i32_e32 v119, 31, v118
	s_waitcnt vmcnt(10)
	v_mfma_f32_16x16x32_bf16 v[64:67], v[222:225], v[32:35], 0
	global_load_dwordx4 v[222:225], v[210:211], off offset:192
	v_lshlrev_b32_e32 v107, 5, v112
	v_mad_u64_u32 v[134:135], s[14:15], v118, s23, v[104:105]
	s_waitcnt vmcnt(10)
	v_mfma_f32_16x16x32_bf16 v[64:67], v[226:229], v[36:39], v[64:67]
	v_lshl_add_u64 v[210:211], v[210:211], 0, s[78:79]
	global_load_dwordx4 v[226:229], v[210:211], off
	v_pk_fma_f32 v[48:49], s[70:71], v[60:61], v[48:49] op_sel_hi:[0,1,1]
	v_pk_mul_f32 v[2:3], v[2:3], v[48:49]
	v_lshlrev_b32_e32 v48, 16, v97
	v_and_b32_e32 v49, 0xffff0000, v97
	v_mul_f32_e32 v57, 0xbfb8aa3b, v48
	v_mul_f32_e32 v0, 0xbfb8aa3b, v49
	v_exp_f32_e32 v57, v57
	v_exp_f32_e32 v0, v0
	s_waitcnt vmcnt(10)
	v_mfma_f32_16x16x32_bf16 v[64:67], v[230:233], v[40:43], v[64:67]
	global_load_dwordx4 v[230:233], v[210:211], off offset:64
	v_add_u32_e32 v73, v81, v107
	v_add_f32_e32 v57, 1.0, v57
	v_add_f32_e32 v0, 1.0, v0
	v_rcp_f32_e32 v58, v57
	v_rcp_f32_e32 v59, v0
	v_pk_fma_f32 v[50:51], s[70:71], v[52:53], v[50:51] op_sel_hi:[0,1,1]
	v_and_b32_e32 v0, 32, v86
	s_waitcnt vmcnt(10)
	v_mfma_f32_16x16x32_bf16 v[64:67], v[234:237], v[44:47], v[64:67]
	global_load_dwordx4 v[234:237], v[210:211], off offset:128
	v_mul_f32_e64 v48, v58, v48
	v_mul_f32_e64 v49, v59, v49
	v_lshlrev_b32_e32 v76, 16, v108
	v_pk_mul_f32 v[96:97], v[48:49], v[50:51]
	v_lshl_add_u64 v[48:49], s[24:25], 0, v[118:119]
	v_lshlrev_b64 v[48:49], 6, v[48:49]
	v_or3_b32 v48, v48, v0, v142
	v_lshlrev_b64 v[48:49], 8, v[48:49]
	v_or_b32_e32 v0, v107, v87
	v_lshl_add_u64 v[60:61], v[116:117], 0, v[48:49]
	v_mad_u32_u24 v112, v85, s22, v0
	s_nop 0
	v_add_u32_e32 v113, 0, v112
	v_add_u32_e32 v112, s26, v112
	ds_read_b64_tr_b16 v[124:125], v113
	ds_read_b64_tr_b16 v[126:127], v112
	s_waitcnt lgkmcnt(0)
	v_add_u32_e32 v0, v89, v0
	ds_read_b128 v[130:133], v106 offset:62464
	v_add_u32_e32 v112, 0, v0
	v_add_u32_e32 v0, s26, v0
	ds_read_b64_tr_b16 v[148:149], v112
	ds_read_b64_tr_b16 v[150:151], v0
	s_waitcnt lgkmcnt(0)
	ds_read_b32 v0, v91
	ds_read_b64 v[74:75], v73
	ds_read_b128 v[152:155], v106 offset:62528
	s_waitcnt lgkmcnt(3)
	v_mfma_f32_16x16x32_bf16 v[68:71], v[124:127], v[130:133], 0
	v_and_b32_e32 v77, 0xffff0000, v108
	s_waitcnt lgkmcnt(2)
	v_mul_f32_e32 v0, 0x3fb8aa3b, v0
	v_exp_f32_e32 v0, v0
	s_waitcnt lgkmcnt(0)
	v_mfma_f32_16x16x32_bf16 v[68:71], v[148:151], v[152:155], v[68:71]
	v_mul_f32_e32 v73, 0xbfb8aa3b, v76
	v_exp_f32_e32 v73, v73
	v_lshlrev_b32_e32 v78, 16, v74
	v_and_b32_e32 v79, 0xffff0000, v74
	s_waitcnt vmcnt(10)
	v_mfma_f32_16x16x32_bf16 v[48:51], v[238:241], v[32:35], 0
	global_load_dwordx4 v[238:241], v[210:211], off offset:192
	s_nop 1
	v_fma_f32 v64, v64, v0, v68
	v_fma_f32 v65, v65, v0, v69
	v_mul_f32_e32 v68, 0xbfb8aa3b, v77
	v_exp_f32_e32 v68, v68
	v_add_f32_e32 v73, 1.0, v73
	v_rcp_f32_e32 v106, v73
	v_pk_fma_f32 v[66:67], v[66:67], v[0:1], v[70:71] op_sel_hi:[1,0,1]
	v_add_f32_e32 v68, 1.0, v68
	v_rcp_f32_e32 v107, v68
	v_ashrrev_i32_e32 v126, 2, v128
	v_ashrrev_i32_e32 v127, 31, v126
	s_waitcnt vmcnt(10)
; #define LAS __attribute__((address_space(3)))
; __device__ __forceinline__ float bflo(unsigned w) { return __uint_as_float(w << 16); }
; __device__ __forceinline__ float bfhi(unsigned w) { return __uint_as_float(w & 0xffff0000u); }
; __device__ __forceinline__ float siluf_(float x) { return x * __builtin_amdgcn_rcpf(1.0f + __expf(-x)); }
; #define MFMA16(a, b, c) __builtin_amdgcn_mfma_f32_16x16x32_bf16((a), (b), (c), 0, 0, 0)
; __device__ void m2_c_unit(LAS unsigned char* lds, KP& P_, int l, int bc, int grp) {
;     ...
;       for (int i = 0; i < 6; ++i) { const int pt = ph * 6 + i, hh = pt >> 2, head = grp * 3 + hh;
;           f32x4 ad = (f32x4){0.f, 0.f, 0.f, 0.f}, ao = (f32x4){0.f, 0.f, 0.f, 0.f};
;           bf16x8 hc[4];
; #pragma unroll
;           for (int ks = 0; ks < 4; ++ks) hc[ks] = hf[ks];
;           if (i < 5) { const int pn = pt + 1;
; #pragma unroll
;               for (int ks = 0; ks < 4; ++ks) hf[ks] = *(const bf16x8*)(stm + (((size_t)bc * 6 + grp * 3 + (pn >> 2)) * 64 + (pn & 3) * 16 + fr) * 128 + ks * 32 + fq * 8); }
; #pragma unroll
;           for (int ks = 0; ks < 2; ++ks) { const unsigned ta = xn_base + (unsigned)((32 * ks + 8 * fq + (fr >> 2)) * 400 + (16 * pt + 4 * (fr & 3)) * 2);
;               const bf16x8 a = tr_frag(ta, ta + 1600u), b = *(const LAS bf16x8*)(PH + hh * 4608 + tq * 72 + ks * 32 + fq * 8); ad = MFMA16(a, b, ad); }
; #pragma unroll
;           for (int ks = 0; ks < 4; ++ks) ao = MFMA16(hc[ks], cf[ks], ao);
;           const float ea = __expf(acs[hh * 64 + tq]), dsk = p.in[9][l * 6 + head]; const int pch = pt * 16 + fq * 4;
;           const float zv[4] = {bflo(zraw[i].x), bfhi(zraw[i].x), bflo(zraw[i].y), bfhi(zraw[i].y)};
;           f32x4 y;
;           const u32x2 xraw = *(const LAS u32x2*)(XN + tq * 200 + pch); const float xsv[4] = {bflo(xraw.x), bfhi(xraw.x), bflo(xraw.y), bfhi(xraw.y)};
; #pragma unroll
;           for (int j = 0; j < 4; ++j) { y[j] = (ad[j] + ea * ao[j] + dsk * xsv[j]) * siluf_(zv[j]); ssq += y[j] * y[j]; }
;           yv[i] = y; }
	v_mfma_f32_16x16x32_bf16 v[48:51], v[242:245], v[36:39], v[48:51]
	v_lshl_add_u64 v[210:211], v[210:211], 0, s[78:79]
	global_load_dwordx4 v[242:245], v[210:211], off
	v_pk_fma_f32 v[64:65], s[70:71], v[78:79], v[64:65] op_sel_hi:[0,1,1]
	v_pk_mul_f32 v[68:69], v[106:107], v[76:77]
	v_lshlrev_b32_e32 v91, 5, v122
	v_pk_mul_f32 v[106:107], v[68:69], v[64:65]
	v_lshlrev_b32_e32 v64, 16, v109
	v_and_b32_e32 v65, 0xffff0000, v109
	v_mul_f32_e32 v73, 0xbfb8aa3b, v64
	v_mul_f32_e32 v0, 0xbfb8aa3b, v65
	v_exp_f32_e32 v73, v73
	v_exp_f32_e32 v0, v0
	v_lshlrev_b32_e32 v68, 16, v75
	v_and_b32_e32 v69, 0xffff0000, v75
	v_add_f32_e32 v73, 1.0, v73
	v_add_f32_e32 v0, 1.0, v0
	v_rcp_f32_e32 v74, v73
	v_rcp_f32_e32 v75, v0
	v_pk_fma_f32 v[66:67], s[70:71], v[68:69], v[66:67] op_sel_hi:[0,1,1]
	v_and_b32_e32 v0, 48, v84
	s_waitcnt vmcnt(10)
	v_mfma_f32_16x16x32_bf16 v[48:51], v[246:249], v[40:43], v[48:51]
	global_load_dwordx4 v[246:249], v[210:211], off offset:64
	v_mul_f32_e64 v64, v74, v64
	v_mul_f32_e64 v65, v75, v65
	v_add_u32_e32 v56, s13, v118
	v_pk_mul_f32 v[108:109], v[64:65], v[66:67]
	v_lshl_add_u64 v[64:65], s[24:25], 0, v[126:127]
	v_lshlrev_b64 v[64:65], 6, v[64:65]
	v_or3_b32 v64, v64, v0, v142
	v_lshlrev_b64 v[64:65], 8, v[64:65]
	v_or_b32_e32 v0, v91, v87
	v_lshl_add_u64 v[76:77], v[116:117], 0, v[64:65]
	v_mad_u32_u24 v119, v85, s22, v0
	s_nop 0
	v_add_u32_e32 v127, 0, v119
	v_add_u32_e32 v119, s26, v119
	ds_read_b64_tr_b16 v[122:123], v127
	ds_read_b64_tr_b16 v[124:125], v119
	s_waitcnt lgkmcnt(0)
	v_add_u32_e32 v0, v89, v0
	v_ashrrev_i32_e32 v57, 31, v56
	ds_read_b128 v[130:133], v134 offset:62464
	v_add_u32_e32 v119, 0, v0
	v_add_u32_e32 v0, s26, v0
	ds_read_b64_tr_b16 v[148:149], v119
	ds_read_b64_tr_b16 v[150:151], v0
	s_waitcnt lgkmcnt(0)
	v_lshl_add_u64 v[56:57], v[56:57], 2, s[44:45]
	v_lshl_add_u32 v0, v118, 8, v83
	ds_read_b32 v0, v0
	ds_read_b128 v[152:155], v134 offset:62528
	s_waitcnt lgkmcnt(2)
	v_mfma_f32_16x16x32_bf16 v[52:55], v[122:125], v[130:133], 0
	v_add_u32_e32 v57, v81, v91
	ds_read_b64 v[58:59], v57
	s_waitcnt lgkmcnt(2)
	v_mul_f32_e32 v0, 0x3fb8aa3b, v0
	s_waitcnt vmcnt(10)
	v_mfma_f32_16x16x32_bf16 v[48:51], v[162:165], v[44:47], v[48:51]
	global_load_dwordx4 v[162:165], v[210:211], off offset:128
	v_exp_f32_e32 v0, v0
	v_lshlrev_b32_e32 v60, 16, v120
	v_and_b32_e32 v61, 0xffff0000, v120
	s_waitcnt lgkmcnt(1)
	v_mfma_f32_16x16x32_bf16 v[52:55], v[148:151], v[152:155], v[52:55]
	v_mul_f32_e32 v57, 0xbfb8aa3b, v60
	v_exp_f32_e32 v57, v57
	s_waitcnt lgkmcnt(0)
	v_lshlrev_b32_e32 v62, 16, v58
	v_and_b32_e32 v63, 0xffff0000, v58
	s_waitcnt vmcnt(10)
	v_mfma_f32_16x16x32_bf16 v[64:67], v[166:169], v[32:35], 0
	global_load_dwordx4 v[166:169], v[210:211], off offset:192
	s_nop 0
	v_fma_f32 v48, v48, v0, v52
	v_fma_f32 v49, v49, v0, v53
	v_mul_f32_e32 v52, 0xbfb8aa3b, v61
	v_exp_f32_e32 v52, v52
	v_add_f32_e32 v57, 1.0, v57
	v_rcp_f32_e32 v118, v57
	v_pk_fma_f32 v[50:51], v[50:51], v[0:1], v[54:55] op_sel_hi:[1,0,1]
	v_add_f32_e32 v52, 1.0, v52
	v_rcp_f32_e32 v119, v52
	v_ashrrev_i32_e32 v132, 2, v146
	v_ashrrev_i32_e32 v133, 31, v132
	s_waitcnt vmcnt(10)
	v_mfma_f32_16x16x32_bf16 v[64:67], v[184:187], v[36:39], v[64:67]
	v_mul_f32_e64 v52, v118, v60
	v_mul_f32_e64 v53, v119, v61
	v_lshlrev_b32_e32 v91, 5, v128
	v_pk_fma_f32 v[48:49], s[72:73], v[62:63], v[48:49] op_sel_hi:[0,1,1]
	v_pk_mul_f32 v[118:119], v[52:53], v[48:49]
	v_lshlrev_b32_e32 v48, 16, v121
	v_and_b32_e32 v49, 0xffff0000, v121
	v_mul_f32_e32 v57, 0xbfb8aa3b, v48
	v_mul_f32_e32 v0, 0xbfb8aa3b, v49
	v_exp_f32_e32 v57, v57
	v_exp_f32_e32 v0, v0
	v_lshlrev_b32_e32 v52, 16, v59
	v_and_b32_e32 v53, 0xffff0000, v59
	v_add_f32_e32 v57, 1.0, v57
	v_add_f32_e32 v0, 1.0, v0
	v_rcp_f32_e32 v58, v57
	v_rcp_f32_e32 v59, v0
	v_pk_fma_f32 v[50:51], s[72:73], v[52:53], v[50:51] op_sel_hi:[0,1,1]
	v_and_b32_e32 v0, 32, v82
	s_waitcnt vmcnt(9)
	v_mfma_f32_16x16x32_bf16 v[64:67], v[188:191], v[40:43], v[64:67]
	v_mul_f32_e64 v48, v58, v48
	v_mul_f32_e64 v49, v59, v49
	v_add_u32_e32 v72, s13, v126
	v_pk_mul_f32 v[120:121], v[48:49], v[50:51]
	v_lshl_add_u64 v[48:49], s[24:25], 0, v[132:133]
	v_lshlrev_b64 v[48:49], 6, v[48:49]
	v_or3_b32 v48, v48, v0, v142
	v_lshlrev_b64 v[48:49], 8, v[48:49]
	v_or_b32_e32 v0, v91, v87
	v_lshl_add_u64 v[60:61], v[116:117], 0, v[48:49]
	v_mad_u32_u24 v127, v85, s22, v0
	s_nop 0
	v_mad_u64_u32 v[134:135], s[14:15], v126, s23, v[104:105]
	v_add_u32_e32 v133, 0, v127
	v_add_u32_e32 v127, s26, v127
	ds_read_b64_tr_b16 v[128:129], v133
	ds_read_b64_tr_b16 v[130:131], v127
	s_waitcnt lgkmcnt(0)
	v_add_u32_e32 v0, v89, v0
	v_ashrrev_i32_e32 v73, 31, v72
	ds_read_b128 v[148:151], v134 offset:62464
	v_add_u32_e32 v127, 0, v0
	v_add_u32_e32 v0, s26, v0
	ds_read_b64_tr_b16 v[152:153], v127
	ds_read_b64_tr_b16 v[154:155], v0
	s_waitcnt lgkmcnt(0)
	v_lshl_add_u64 v[72:73], v[72:73], 2, s[44:45]
	v_lshl_add_u32 v0, v126, 8, v83
	ds_read_b32 v0, v0
	ds_read_b128 v[156:159], v134 offset:62528
	s_waitcnt lgkmcnt(2)
	v_mfma_f32_16x16x32_bf16 v[68:71], v[128:131], v[148:151], 0
	v_add_u32_e32 v73, v81, v91
	ds_read_b64 v[74:75], v73
	s_waitcnt lgkmcnt(2)
	v_mul_f32_e32 v0, 0x3fb8aa3b, v0
	s_waitcnt vmcnt(8)
	v_mfma_f32_16x16x32_bf16 v[64:67], v[222:225], v[44:47], v[64:67]
	v_exp_f32_e32 v0, v0
	v_lshlrev_b32_e32 v76, 16, v114
	v_and_b32_e32 v77, 0xffff0000, v114
	s_waitcnt lgkmcnt(1)
	v_mfma_f32_16x16x32_bf16 v[68:71], v[152:155], v[156:159], v[68:71]
	v_mul_f32_e32 v73, 0xbfb8aa3b, v76
	v_exp_f32_e32 v73, v73
	s_waitcnt lgkmcnt(0)
	v_lshlrev_b32_e32 v78, 16, v74
	v_and_b32_e32 v79, 0xffff0000, v74
	s_waitcnt vmcnt(7)
; #define LAS __attribute__((address_space(3)))
; __device__ __forceinline__ float bflo(unsigned w) { return __uint_as_float(w << 16); }
; __device__ __forceinline__ float bfhi(unsigned w) { return __uint_as_float(w & 0xffff0000u); }
; __device__ __forceinline__ float siluf_(float x) { return x * __builtin_amdgcn_rcpf(1.0f + __expf(-x)); }
; #define MFMA16(a, b, c) __builtin_amdgcn_mfma_f32_16x16x32_bf16((a), (b), (c), 0, 0, 0)
; __device__ void m2_c_unit(LAS unsigned char* lds, KP& P_, int l, int bc, int grp) {
;     ...
;       for (int i = 0; i < 6; ++i) { const int pt = ph * 6 + i, hh = pt >> 2, head = grp * 3 + hh;
;           f32x4 ad = (f32x4){0.f, 0.f, 0.f, 0.f}, ao = (f32x4){0.f, 0.f, 0.f, 0.f};
;           bf16x8 hc[4];
; #pragma unroll
;           for (int ks = 0; ks < 4; ++ks) hc[ks] = hf[ks];
;           if (i < 5) { const int pn = pt + 1;
; #pragma unroll
;               for (int ks = 0; ks < 4; ++ks) hf[ks] = *(const bf16x8*)(stm + (((size_t)bc * 6 + grp * 3 + (pn >> 2)) * 64 + (pn & 3) * 16 + fr) * 128 + ks * 32 + fq * 8); }
; #pragma unroll
;           for (int ks = 0; ks < 2; ++ks) { const unsigned ta = xn_base + (unsigned)((32 * ks + 8 * fq + (fr >> 2)) * 400 + (16 * pt + 4 * (fr & 3)) * 2);
;               const bf16x8 a = tr_frag(ta, ta + 1600u), b = *(const LAS bf16x8*)(PH + hh * 4608 + tq * 72 + ks * 32 + fq * 8); ad = MFMA16(a, b, ad); }
; #pragma unroll
;           for (int ks = 0; ks < 4; ++ks) ao = MFMA16(hc[ks], cf[ks], ao);
;           const float ea = __expf(acs[hh * 64 + tq]), dsk = p.in[9][l * 6 + head]; const int pch = pt * 16 + fq * 4;
;           const float zv[4] = {bflo(zraw[i].x), bfhi(zraw[i].x), bflo(zraw[i].y), bfhi(zraw[i].y)};
;           f32x4 y;
;           const u32x2 xraw = *(const LAS u32x2*)(XN + tq * 200 + pch); const float xsv[4] = {bflo(xraw.x), bfhi(xraw.x), bflo(xraw.y), bfhi(xraw.y)};
; #pragma unroll
;           for (int j = 0; j < 4; ++j) { y[j] = (ad[j] + ea * ao[j] + dsk * xsv[j]) * siluf_(zv[j]); ssq += y[j] * y[j]; }
;           yv[i] = y; }
	v_mfma_f32_16x16x32_bf16 v[48:51], v[226:229], v[32:35], 0
	s_nop 0
	v_fma_f32 v64, v64, v0, v68
	v_fma_f32 v65, v65, v0, v69
	v_mul_f32_e32 v68, 0xbfb8aa3b, v77
	v_exp_f32_e32 v68, v68
	v_add_f32_e32 v73, 1.0, v73
	v_rcp_f32_e32 v126, v73
	v_pk_fma_f32 v[66:67], v[66:67], v[0:1], v[70:71] op_sel_hi:[1,0,1]
	v_add_f32_e32 v68, 1.0, v68
	v_rcp_f32_e32 v127, v68
	v_ashrrev_i32_e32 v134, 2, v145
	v_ashrrev_i32_e32 v135, 31, v134
	s_waitcnt vmcnt(6)
	v_mfma_f32_16x16x32_bf16 v[48:51], v[230:233], v[36:39], v[48:51]
	v_mul_f32_e64 v68, v126, v76
	v_mul_f32_e64 v69, v127, v77
	v_lshlrev_b32_e32 v91, 5, v146
	v_pk_mul_f32 v[98:99], v[2:3], v[2:3]
	s_waitcnt vmcnt(5)
	v_mfma_f32_16x16x32_bf16 v[48:51], v[234:237], v[40:43], v[48:51]
	v_pk_fma_f32 v[64:65], s[72:73], v[78:79], v[64:65] op_sel_hi:[0,1,1]
	v_pk_mul_f32 v[126:127], v[68:69], v[64:65]
	v_lshlrev_b32_e32 v64, 16, v115
	v_and_b32_e32 v65, 0xffff0000, v115
	v_mul_f32_e32 v73, 0xbfb8aa3b, v64
	v_mul_f32_e32 v0, 0xbfb8aa3b, v65
	v_exp_f32_e32 v73, v73
	v_exp_f32_e32 v0, v0
	v_lshlrev_b32_e32 v68, 16, v75
	v_and_b32_e32 v69, 0xffff0000, v75
	v_add_f32_e32 v73, 1.0, v73
	v_add_f32_e32 v0, 1.0, v0
	v_rcp_f32_e32 v74, v73
	v_rcp_f32_e32 v75, v0
	v_pk_fma_f32 v[66:67], s[72:73], v[68:69], v[66:67] op_sel_hi:[0,1,1]
	v_and_b32_e32 v0, 48, v80
	v_add_u32_e32 v56, s13, v132
	v_pk_mul_f32 v[64:65], v[74:75], v[64:65]
	v_ashrrev_i32_e32 v57, 31, v56
	v_pk_mul_f32 v[114:115], v[64:65], v[66:67]
	v_lshl_add_u64 v[64:65], s[24:25], 0, v[134:135]
	v_lshlrev_b64 v[64:65], 6, v[64:65]
	v_or3_b32 v64, v64, v0, v142
	v_lshlrev_b64 v[64:65], 8, v[64:65]
	v_lshl_add_u64 v[76:77], v[116:117], 0, v[64:65]
	v_or_b32_e32 v0, v91, v87
	v_mad_u64_u32 v[116:117], s[14:15], v132, s23, v[104:105]
	v_mad_u32_u24 v117, v85, s22, v0
	s_nop 0
	v_add_u32_e32 v133, 0, v117
	v_add_u32_e32 v117, s26, v117
	ds_read_b64_tr_b16 v[146:147], v133
	ds_read_b64_tr_b16 v[148:149], v117
	s_waitcnt lgkmcnt(0)
	v_add_u32_e32 v0, v89, v0
	ds_read_b128 v[150:153], v116 offset:62464
	v_add_u32_e32 v117, 0, v0
	v_add_u32_e32 v0, s26, v0
	ds_read_b64_tr_b16 v[154:155], v117
	ds_read_b64_tr_b16 v[156:157], v0
	s_waitcnt lgkmcnt(0)
	v_lshl_add_u64 v[56:57], v[56:57], 2, s[44:45]
	v_lshl_add_u32 v0, v132, 8, v83
	ds_read_b32 v0, v0
	ds_read_b128 v[158:161], v116 offset:62528
	s_waitcnt lgkmcnt(2)
	v_mfma_f32_16x16x32_bf16 v[52:55], v[146:149], v[150:153], 0
	v_add_u32_e32 v57, v81, v91
	ds_read_b64 v[58:59], v57
	s_waitcnt lgkmcnt(2)
	v_mul_f32_e32 v0, 0x3fb8aa3b, v0
	s_waitcnt vmcnt(4)
	v_mfma_f32_16x16x32_bf16 v[48:51], v[238:241], v[44:47], v[48:51]
	v_exp_f32_e32 v0, v0
	v_lshlrev_b32_e32 v60, 16, v102
	v_and_b32_e32 v61, 0xffff0000, v102
	s_waitcnt lgkmcnt(1)
	v_mfma_f32_16x16x32_bf16 v[52:55], v[154:157], v[158:161], v[52:55]
	v_mul_f32_e32 v57, 0xbfb8aa3b, v60
	v_exp_f32_e32 v57, v57
	s_waitcnt lgkmcnt(0)
	v_lshlrev_b32_e32 v62, 16, v58
	v_and_b32_e32 v63, 0xffff0000, v58
	s_waitcnt vmcnt(3)
	v_mfma_f32_16x16x32_bf16 v[32:35], v[242:245], v[32:35], 0
	s_nop 0
	v_fma_f32 v48, v48, v0, v52
	v_fma_f32 v49, v49, v0, v53
	v_mul_f32_e32 v52, 0xbfb8aa3b, v61
	v_exp_f32_e32 v52, v52
	v_add_f32_e32 v57, 1.0, v57
	v_rcp_f32_e32 v116, v57
	v_pk_fma_f32 v[50:51], v[50:51], v[0:1], v[54:55] op_sel_hi:[1,0,1]
	v_add_f32_e32 v52, 1.0, v52
	v_rcp_f32_e32 v117, v52
	s_waitcnt vmcnt(2)
	v_mfma_f32_16x16x32_bf16 v[32:35], v[246:249], v[36:39], v[32:35]
	v_lshlrev_b32_e32 v91, 5, v145
	v_lshlrev_b32_e32 v58, 16, v59
	v_pk_mul_f32 v[52:53], v[116:117], v[60:61]
	v_pk_fma_f32 v[48:49], s[74:75], v[62:63], v[48:49] op_sel_hi:[0,1,1]
	v_pk_mul_f32 v[48:49], v[52:53], v[48:49]
	v_lshlrev_b32_e32 v52, 16, v103
	v_and_b32_e32 v53, 0xffff0000, v103
	v_mul_f32_e32 v57, 0xbfb8aa3b, v52
	v_mul_f32_e32 v0, 0xbfb8aa3b, v53
	v_exp_f32_e32 v57, v57
	v_exp_f32_e32 v0, v0
	v_and_b32_e32 v59, 0xffff0000, v59
	s_waitcnt vmcnt(1)
	v_mfma_f32_16x16x32_bf16 v[32:35], v[162:165], v[40:43], v[32:35]
	v_add_f32_e32 v57, 1.0, v57
	v_add_f32_e32 v0, 1.0, v0
	v_rcp_f32_e32 v60, v57
	v_rcp_f32_e32 v61, v0
	v_or_b32_e32 v0, v91, v87
	v_pk_fma_f32 v[50:51], s[74:75], v[58:59], v[50:51] op_sel_hi:[0,1,1]
	v_mad_u32_u24 v56, v85, s22, v0
	v_add_u32_e32 v40, s13, v134
	v_pk_mul_f32 v[52:53], v[60:61], v[52:53]
	v_mad_u64_u32 v[102:103], s[14:15], v134, s23, v[104:105]
	v_add_u32_e32 v60, 0, v56
	v_add_u32_e32 v61, s26, v56
	ds_read_b64_tr_b16 v[56:57], v60
	ds_read_b64_tr_b16 v[58:59], v61
	s_waitcnt lgkmcnt(0)
; #define LAS __attribute__((address_space(3)))
; __device__ __forceinline__ float bflo(unsigned w) { return __uint_as_float(w << 16); }
; __device__ __forceinline__ float bfhi(unsigned w) { return __uint_as_float(w & 0xffff0000u); }
; __device__ __forceinline__ float siluf_(float x) { return x * __builtin_amdgcn_rcpf(1.0f + __expf(-x)); }
; #define MFMA16(a, b, c) __builtin_amdgcn_mfma_f32_16x16x32_bf16((a), (b), (c), 0, 0, 0)
; __device__ void m2_c_unit(LAS unsigned char* lds, KP& P_, int l, int bc, int grp) {
;     ...
;       for (int i = 0; i < 6; ++i) { const int pt = ph * 6 + i, hh = pt >> 2, head = grp * 3 + hh;
;           f32x4 ad = (f32x4){0.f, 0.f, 0.f, 0.f}, ao = (f32x4){0.f, 0.f, 0.f, 0.f};
;           bf16x8 hc[4];
; #pragma unroll
;           for (int ks = 0; ks < 4; ++ks) hc[ks] = hf[ks];
;           if (i < 5) { const int pn = pt + 1;
; #pragma unroll
;               for (int ks = 0; ks < 4; ++ks) hf[ks] = *(const bf16x8*)(stm + (((size_t)bc * 6 + grp * 3 + (pn >> 2)) * 64 + (pn & 3) * 16 + fr) * 128 + ks * 32 + fq * 8); }
; #pragma unroll
;           for (int ks = 0; ks < 2; ++ks) { const unsigned ta = xn_base + (unsigned)((32 * ks + 8 * fq + (fr >> 2)) * 400 + (16 * pt + 4 * (fr & 3)) * 2);
;               const bf16x8 a = tr_frag(ta, ta + 1600u), b = *(const LAS bf16x8*)(PH + hh * 4608 + tq * 72 + ks * 32 + fq * 8); ad = MFMA16(a, b, ad); }
; #pragma unroll
;           for (int ks = 0; ks < 4; ++ks) ao = MFMA16(hc[ks], cf[ks], ao);
;           const float ea = __expf(acs[hh * 64 + tq]), dsk = p.in[9][l * 6 + head]; const int pch = pt * 16 + fq * 4;
;           const float zv[4] = {bflo(zraw[i].x), bfhi(zraw[i].x), bflo(zraw[i].y), bfhi(zraw[i].y)};
;           f32x4 y;
;           const u32x2 xraw = *(const LAS u32x2*)(XN + tq * 200 + pch); const float xsv[4] = {bflo(xraw.x), bfhi(xraw.x), bflo(xraw.y), bfhi(xraw.y)};
; #pragma unroll
;           for (int j = 0; j < 4; ++j) { y[j] = (ad[j] + ea * ao[j] + dsk * xsv[j]) * siluf_(zv[j]); ssq += y[j] * y[j]; }
;           yv[i] = y; }
;       ssq += __shfl_xor(ssq, 16); ssq += __shfl_xor(ssq, 32);
;       if (fq == 0) ss[tq * 2 + ph] = ssq; }
	v_add_u32_e32 v0, v89, v0
	v_ashrrev_i32_e32 v41, 31, v40
	ds_read_b128 v[60:63], v102 offset:62464
	v_add_u32_e32 v85, 0, v0
	v_add_u32_e32 v0, s26, v0
	ds_read_b64_tr_b16 v[146:147], v85
	ds_read_b64_tr_b16 v[148:149], v0
	s_waitcnt lgkmcnt(0)
	v_lshl_add_u64 v[40:41], v[40:41], 2, s[44:45]
	v_lshl_add_u32 v0, v134, 8, v83
	ds_read_b32 v0, v0
	ds_read_b128 v[150:153], v102 offset:62528
	s_waitcnt lgkmcnt(2)
	v_mfma_f32_16x16x32_bf16 v[36:39], v[56:59], v[60:63], 0
	v_add_u32_e32 v41, v81, v91
	ds_read_b64 v[42:43], v41
	s_waitcnt lgkmcnt(2)
	v_mul_f32_e32 v0, 0x3fb8aa3b, v0
	s_waitcnt vmcnt(0)
	v_mfma_f32_16x16x32_bf16 v[32:35], v[166:169], v[44:47], v[32:35]
	v_exp_f32_e32 v0, v0
	v_lshlrev_b32_e32 v44, 16, v94
	v_and_b32_e32 v45, 0xffff0000, v94
	s_waitcnt lgkmcnt(1)
	v_mfma_f32_16x16x32_bf16 v[36:39], v[146:149], v[150:153], v[36:39]
	v_mul_f32_e32 v41, 0xbfb8aa3b, v44
	v_exp_f32_e32 v41, v41
	s_waitcnt lgkmcnt(0)
	v_lshlrev_b32_e32 v46, 16, v42
	v_and_b32_e32 v47, 0xffff0000, v42
	v_pk_mul_f32 v[100:101], v[96:97], v[96:97]
	s_nop 1
	v_pk_fma_f32 v[32:33], v[32:33], v[0:1], v[36:37] op_sel_hi:[1,0,1]
	v_mul_f32_e32 v36, 0xbfb8aa3b, v45
	v_exp_f32_e32 v36, v36
	v_add_f32_e32 v41, 1.0, v41
	v_rcp_f32_e32 v56, v41
	v_pk_fma_f32 v[34:35], v[34:35], v[0:1], v[38:39] op_sel_hi:[1,0,1]
	v_add_f32_e32 v36, 1.0, v36
	v_rcp_f32_e32 v57, v36
	v_pk_mul_f32 v[110:111], v[106:107], v[106:107]
	v_pk_mul_f32 v[112:113], v[108:109], v[108:109]
	v_pk_mul_f32 v[122:123], v[118:119], v[118:119]
	v_pk_mul_f32 v[36:37], v[56:57], v[44:45]
	v_and_b32_e32 v45, 0xffff0000, v95
	v_mul_f32_e32 v0, 0xbfb8aa3b, v45
	v_exp_f32_e32 v0, v0
	v_lshlrev_b32_e32 v44, 16, v95
	v_pk_mul_f32 v[124:125], v[120:121], v[120:121]
	v_pk_mul_f32 v[128:129], v[126:127], v[126:127]
	v_add_f32_e32 v0, 1.0, v0
	v_pk_mul_f32 v[130:131], v[114:115], v[114:115]
	v_pk_mul_f32 v[54:55], v[48:49], v[48:49]
	v_pk_mul_f32 v[50:51], v[52:53], v[50:51]
	v_lshlrev_b32_e32 v42, 16, v43
	v_pk_mul_f32 v[52:53], v[50:51], v[50:51]
	v_and_b32_e32 v43, 0xffff0000, v43
	v_pk_fma_f32 v[32:33], s[74:75], v[46:47], v[32:33] op_sel_hi:[0,1,1]
	v_rcp_f32_e32 v47, v0
	v_add_f32_e32 v0, v98, v99
	v_add_f32_e32 v0, v100, v0
	v_add_f32_e32 v0, v101, v0
	v_add_f32_e32 v0, v0, v110
	v_add_f32_e32 v0, v111, v0
	v_add_f32_e32 v0, v112, v0
	v_add_f32_e32 v0, v113, v0
	v_add_f32_e32 v0, v0, v122
	v_mul_f32_e32 v41, 0xbfb8aa3b, v44
	v_add_f32_e32 v0, v123, v0
	v_exp_f32_e32 v41, v41
	v_add_f32_e32 v0, v124, v0
	v_add_f32_e32 v0, v125, v0
	v_add_f32_e32 v0, v0, v128
	v_add_f32_e32 v0, v129, v0
	v_add_f32_e32 v41, 1.0, v41
	v_add_f32_e32 v0, v130, v0
	v_rcp_f32_e32 v46, v41
	v_add_f32_e32 v0, v131, v0
	v_add_f32_e32 v0, v0, v54
	v_add_f32_e32 v0, v55, v0
	v_pk_mul_f32 v[32:33], v[36:37], v[32:33]
	v_add_f32_e32 v0, v52, v0
	v_pk_mul_f32 v[36:37], v[32:33], v[32:33]
	v_pk_fma_f32 v[34:35], s[74:75], v[42:43], v[34:35] op_sel_hi:[0,1,1]
	v_pk_mul_f32 v[38:39], v[46:47], v[44:45]
	v_add_f32_e32 v0, v53, v0
	v_pk_mul_f32 v[34:35], v[38:39], v[34:35]
	v_add_f32_e32 v0, v0, v36
	v_xor_b32_e32 v36, 16, v204
	v_pk_mul_f32 v[38:39], v[34:35], v[34:35]
	v_add_f32_e32 v0, v37, v0
	v_cmp_lt_i32_e32 vcc, v36, v206
	v_add_f32_e32 v0, v38, v0
	v_add_f32_e32 v0, v39, v0
	v_cndmask_b32_e32 v36, v204, v36, vcc
	v_lshlrev_b32_e32 v36, 2, v36
	ds_bpermute_b32 v36, v36, v0
	s_waitcnt lgkmcnt(0)
	v_add_f32_e32 v36, v0, v36
	v_xor_b32_e32 v0, 32, v204
	v_cmp_lt_i32_e32 vcc, v0, v206
	s_nop 1
	v_cndmask_b32_e32 v0, v204, v0, vcc
	v_lshlrev_b32_e32 v0, 2, v0
	ds_bpermute_b32 v37, v0, v36
	v_cmp_eq_u32_e32 vcc, 0, v141
	v_lshlrev_b32_e32 v0, 3, v144
	s_and_saveexec_b64 s[14:15], vcc
	s_cbranch_execz .LBB0_304
	s_waitcnt lgkmcnt(0)
	v_add_f32_e32 v36, v36, v37
	v_lshlrev_b32_e32 v37, 2, v143
	v_readlane_b32 s12, v255, 11
	s_nop 1
	v_add3_u32 v37, s12, v0, v37
	ds_write_b32 v37, v36
	s_branch .LBB0_304
